# MIX lists: the 128 item blocks that share CUs with the sample chains get the shortest lists (diff-sample + small items); the other 128 attention blocks take two std-sample items
# speedup vs baseline: 1.0051x; 1.0002x over previous
.Lms_y:
	s_cmpk_lt_u32 s0, 0x180
	s_cbranch_scc0 .Lms_y2
	s_movk_i32 s2, 424
	s_cmpk_eq_u32 s1, 128
	s_cbranch_scc1 .Lms_set
	s_movk_i32 s2, 552
	s_cmpk_eq_u32 s1, 424
	s_cbranch_scc1 .Lms_set
	s_movk_i32 s2, 680
	s_cmpk_eq_u32 s1, 552
	s_cbranch_scc1 .Lms_set
	s_movk_i32 s2, 936
	s_cmpk_eq_u32 s1, 680
	s_cbranch_scc1 .Lms_set
	s_branch .LBB0_1139
.Lms_y2:
	s_movk_i32 s2, 680
	s_cmpk_eq_u32 s1, 128
	s_cbranch_scc1 .Lms_set
	s_movk_i32 s2, 936
	s_cmpk_eq_u32 s1, 680
	s_cbranch_scc1 .Lms_set
	s_cmpk_eq_u32 s1, 936
	s_cbranch_scc0 .LBB0_1139
	s_movk_i32 s2, 256
	s_cmpk_lt_u32 s0, 0x1a8
	s_cbranch_scc0 .LBB0_1139
